# P9 FFN-in epilogue: hoist 8 serialized ss[row] loads to epilogue top, drop per-step vmcnt(0)
# speedup vs baseline: 1.0104x; 1.0104x over previous
.LBB0_1211:
	s_lshl_b32 s19, s6, 8
	v_add_u32_e32 v164, s19, v172
	s_addk_i32 s19, 0xe000
	s_lshr_b32 s19, s19, 12
	s_add_i32 s19, s19, 1
	v_ashrrev_i32_e32 v165, 31, v164
	s_cmp_gt_i32 s6, 31
	v_lshl_add_u64 v[166:167], v[164:165], 2, s[14:15]
	s_cselect_b32 s6, s19, 0
	global_load_dword v198, v[166:167], off
	global_load_dword v199, v[166:167], off offset:64
	global_load_dword v200, v[166:167], off offset:128
	global_load_dword v201, v[166:167], off offset:192
	global_load_dword v202, v[166:167], off offset:512
	global_load_dword v203, v[166:167], off offset:576
	global_load_dword v204, v[166:167], off offset:640
	global_load_dword v205, v[166:167], off offset:704
	s_mul_hi_u32 s19, s6, 0xb000
	s_mul_i32 s6, s6, 0xb000
	s_add_u32 s6, s12, s6
	s_addc_u32 s19, s13, s19
	s_lshl_b32 s26, s7, 8
	s_ashr_i32 s27, s26, 31
	s_lshl_b64 s[26:27], s[26:27], 2
	s_add_u32 s6, s6, s26
	s_addc_u32 s19, s19, s27
	s_add_u32 s26, s6, s47
	s_addc_u32 s27, s19, 0
	global_load_dwordx4 v[102:105], v179, s[26:27]
	global_load_dwordx4 v[110:113], v179, s[26:27] offset:512
	global_load_dwordx4 v[98:101], v179, s[26:27] offset:16
	global_load_dwordx4 v[106:109], v179, s[26:27] offset:528
	v_or_b32_e32 v184, 16, v164
	v_ashrrev_i32_e32 v185, 31, v184
	v_lshl_add_u64 v[186:187], v[184:185], 2, s[14:15]
	v_lshl_or_b32 v170, s7, 7, v174
	v_mov_b64_e32 v[168:169], s[54:55]
	v_ashrrev_i32_e32 v171, 31, v170
	v_mad_i64_i32 v[182:183], s[6:7], v164, s49, v[168:169]
	v_lshlrev_b64 v[170:171], 1, v[170:171]
	v_lshl_add_u64 v[182:183], v[182:183], 0, v[170:171]
	s_waitcnt vmcnt(0)
	v_fmamk_f32 v165, v198, 0x3a000000, v180
	v_mul_f32_e32 v181, 0x4b800000, v165
	v_cmp_gt_f32_e32 vcc, s48, v165
	s_nop 1
	v_cndmask_b32_e32 v165, v165, v181, vcc
	v_rsq_f32_e32 v165, v165
	s_nop 0
	v_mul_f32_e32 v181, 0x45800000, v165
	v_cndmask_b32_e32 v188, v165, v181, vcc
	v_pk_fma_f32 v[142:143], v[142:143], v[188:189], v[102:103] op_sel_hi:[1,0,1]
	v_pk_fma_f32 v[138:139], v[138:139], v[188:189], v[98:99] op_sel_hi:[1,0,1]
	v_pk_fma_f32 v[144:145], v[144:145], v[188:189], v[104:105] op_sel_hi:[1,0,1]
	v_pk_fma_f32 v[140:141], v[140:141], v[188:189], v[100:101] op_sel_hi:[1,0,1]
	v_pk_fma_f32 v[134:135], v[134:135], v[188:189], v[110:111] op_sel_hi:[1,0,1]
	v_pk_fma_f32 v[130:131], v[130:131], v[188:189], v[106:107] op_sel_hi:[1,0,1]
	v_pk_fma_f32 v[136:137], v[136:137], v[188:189], v[112:113] op_sel_hi:[1,0,1]
	v_pk_fma_f32 v[132:133], v[132:133], v[188:189], v[108:109] op_sel_hi:[1,0,1]
	v_mul_f32_e32 v165, 0xbfb8aa3b, v142
	v_mul_f32_e32 v181, 0xbfb8aa3b, v143
	v_mul_f32_e32 v185, 0xbfb8aa3b, v138
	v_mul_f32_e32 v188, 0xbfb8aa3b, v139
	v_mul_f32_e32 v189, 0xbfb8aa3b, v144
	v_mul_f32_e32 v190, 0xbfb8aa3b, v145
	v_mul_f32_e32 v191, 0xbfb8aa3b, v140
	v_mul_f32_e32 v192, 0xbfb8aa3b, v141
	v_exp_f32_e32 v165, v165
	v_exp_f32_e32 v181, v181
	v_exp_f32_e32 v185, v185
	v_exp_f32_e32 v188, v188
	v_exp_f32_e32 v189, v189
	v_exp_f32_e32 v190, v190
	v_exp_f32_e32 v191, v191
	v_exp_f32_e32 v192, v192
	v_add_f32_e32 v165, 1.0, v165
	v_add_f32_e32 v181, 1.0, v181
	v_add_f32_e32 v185, 1.0, v185
	v_add_f32_e32 v193, 1.0, v188
	v_add_f32_e32 v194, 1.0, v189
	v_add_f32_e32 v195, 1.0, v190
	v_add_f32_e32 v196, 1.0, v191
	v_add_f32_e32 v197, 1.0, v192
	v_rcp_f32_e32 v188, v165
	v_rcp_f32_e32 v189, v181
	v_rcp_f32_e32 v190, v185
	v_rcp_f32_e32 v191, v193
	v_rcp_f32_e32 v192, v194
	v_rcp_f32_e32 v193, v195
	v_rcp_f32_e32 v194, v196
	v_rcp_f32_e32 v195, v197
	v_pk_mul_f32 v[142:143], v[142:143], v[188:189]
	v_pk_mul_f32 v[138:139], v[138:139], v[190:191]
	v_pk_mul_f32 v[144:145], v[144:145], v[192:193]
	v_pk_mul_f32 v[140:141], v[140:141], v[194:195]
	v_pk_mul_f32 v[134:135], v[134:135], v[142:143]
	v_pk_mul_f32 v[138:139], v[130:131], v[138:139]
	v_pk_mul_f32 v[136:137], v[136:137], v[144:145]
	v_pk_mul_f32 v[140:141], v[132:133], v[140:141]
	v_cvt_pk_bf16_f32 v130, v134, v135
	v_cvt_pk_bf16_f32 v131, v136, v137
	v_cvt_pk_bf16_f32 v132, v138, v139
	v_cvt_pk_bf16_f32 v133, v140, v141
	global_store_dwordx4 v[182:183], v[130:133], off nt
	s_nop 0
	s_nop 0
	v_or_b32_e32 v130, 32, v164
	v_mad_i64_i32 v[132:133], s[6:7], v184, s49, v[168:169]
	v_lshl_add_u64 v[132:133], v[132:133], 0, v[170:171]
	s_nop 0
	v_fmamk_f32 v131, v199, 0x3a000000, v180
	v_mul_f32_e32 v134, 0x4b800000, v131
	v_cmp_gt_f32_e32 vcc, s48, v131
	s_nop 1
	v_cndmask_b32_e32 v131, v131, v134, vcc
	v_rsq_f32_e32 v136, v131
	v_ashrrev_i32_e32 v131, 31, v130
	v_lshl_add_u64 v[134:135], v[130:131], 2, s[14:15]
	v_mul_f32_e32 v131, 0x45800000, v136
	v_cndmask_b32_e32 v136, v136, v131, vcc
	v_pk_fma_f32 v[126:127], v[126:127], v[136:137], v[102:103] op_sel_hi:[1,0,1]
	v_pk_fma_f32 v[122:123], v[122:123], v[136:137], v[98:99] op_sel_hi:[1,0,1]
	v_pk_fma_f32 v[128:129], v[128:129], v[136:137], v[104:105] op_sel_hi:[1,0,1]
	v_pk_fma_f32 v[124:125], v[124:125], v[136:137], v[100:101] op_sel_hi:[1,0,1]
	v_pk_fma_f32 v[118:119], v[118:119], v[136:137], v[110:111] op_sel_hi:[1,0,1]
	v_pk_fma_f32 v[114:115], v[114:115], v[136:137], v[106:107] op_sel_hi:[1,0,1]
	v_pk_fma_f32 v[120:121], v[120:121], v[136:137], v[112:113] op_sel_hi:[1,0,1]
	v_pk_fma_f32 v[116:117], v[116:117], v[136:137], v[108:109] op_sel_hi:[1,0,1]
	v_mul_f32_e32 v131, 0xbfb8aa3b, v126
	v_mul_f32_e32 v136, 0xbfb8aa3b, v127
	v_mul_f32_e32 v137, 0xbfb8aa3b, v122
	v_mul_f32_e32 v138, 0xbfb8aa3b, v123
	v_mul_f32_e32 v139, 0xbfb8aa3b, v128
	v_mul_f32_e32 v140, 0xbfb8aa3b, v129
	v_mul_f32_e32 v141, 0xbfb8aa3b, v124
	v_mul_f32_e32 v142, 0xbfb8aa3b, v125
	v_exp_f32_e32 v131, v131
	v_exp_f32_e32 v136, v136
	v_exp_f32_e32 v137, v137
	v_exp_f32_e32 v138, v138
	v_exp_f32_e32 v139, v139
	v_exp_f32_e32 v140, v140
	v_exp_f32_e32 v141, v141
	v_exp_f32_e32 v142, v142
	v_add_f32_e32 v131, 1.0, v131
	v_add_f32_e32 v143, 1.0, v136
	v_add_f32_e32 v144, 1.0, v137
	v_add_f32_e32 v145, 1.0, v138
	v_add_f32_e32 v165, 1.0, v139
	v_add_f32_e32 v181, 1.0, v140
	v_add_f32_e32 v182, 1.0, v141
	v_add_f32_e32 v183, 1.0, v142
	v_rcp_f32_e32 v136, v131
	v_rcp_f32_e32 v137, v143
	v_rcp_f32_e32 v138, v144
	v_rcp_f32_e32 v139, v145
	v_rcp_f32_e32 v140, v165
	v_rcp_f32_e32 v141, v181
	v_rcp_f32_e32 v142, v182
	v_rcp_f32_e32 v143, v183
	v_pk_mul_f32 v[126:127], v[126:127], v[136:137]
	v_pk_mul_f32 v[122:123], v[122:123], v[138:139]
	v_pk_mul_f32 v[128:129], v[128:129], v[140:141]
	v_pk_mul_f32 v[124:125], v[124:125], v[142:143]
	v_pk_mul_f32 v[118:119], v[118:119], v[126:127]
	v_pk_mul_f32 v[122:123], v[114:115], v[122:123]
	v_pk_mul_f32 v[120:121], v[120:121], v[128:129]
	v_pk_mul_f32 v[124:125], v[116:117], v[124:125]
	v_cvt_pk_bf16_f32 v114, v118, v119
	v_cvt_pk_bf16_f32 v115, v120, v121
	v_cvt_pk_bf16_f32 v116, v122, v123
	v_cvt_pk_bf16_f32 v117, v124, v125
	global_store_dwordx4 v[132:133], v[114:117], off nt
	s_nop 0
	s_nop 0
	v_or_b32_e32 v114, 48, v164
	v_mad_i64_i32 v[116:117], s[6:7], v130, s49, v[168:169]
	v_lshl_add_u64 v[116:117], v[116:117], 0, v[170:171]
	s_nop 0
	v_fmamk_f32 v115, v200, 0x3a000000, v180
	v_mul_f32_e32 v118, 0x4b800000, v115
	v_cmp_gt_f32_e32 vcc, s48, v115
	s_nop 1
	v_cndmask_b32_e32 v115, v115, v118, vcc
	v_rsq_f32_e32 v120, v115
	v_ashrrev_i32_e32 v115, 31, v114
	v_lshl_add_u64 v[118:119], v[114:115], 2, s[14:15]
	v_mul_f32_e32 v115, 0x45800000, v120
	v_cndmask_b32_e32 v120, v120, v115, vcc
	v_pk_fma_f32 v[94:95], v[94:95], v[120:121], v[102:103] op_sel_hi:[1,0,1]
	v_pk_fma_f32 v[90:91], v[90:91], v[120:121], v[98:99] op_sel_hi:[1,0,1]
	v_pk_fma_f32 v[96:97], v[96:97], v[120:121], v[104:105] op_sel_hi:[1,0,1]
	v_pk_fma_f32 v[92:93], v[92:93], v[120:121], v[100:101] op_sel_hi:[1,0,1]
	v_pk_fma_f32 v[86:87], v[86:87], v[120:121], v[110:111] op_sel_hi:[1,0,1]
	v_pk_fma_f32 v[82:83], v[82:83], v[120:121], v[106:107] op_sel_hi:[1,0,1]
	v_pk_fma_f32 v[88:89], v[88:89], v[120:121], v[112:113] op_sel_hi:[1,0,1]
	v_pk_fma_f32 v[84:85], v[84:85], v[120:121], v[108:109] op_sel_hi:[1,0,1]
	v_mul_f32_e32 v115, 0xbfb8aa3b, v94
	v_mul_f32_e32 v120, 0xbfb8aa3b, v95
	v_mul_f32_e32 v121, 0xbfb8aa3b, v90
	v_mul_f32_e32 v122, 0xbfb8aa3b, v91
	v_mul_f32_e32 v123, 0xbfb8aa3b, v96
	v_mul_f32_e32 v124, 0xbfb8aa3b, v97
	v_mul_f32_e32 v125, 0xbfb8aa3b, v92
	v_mul_f32_e32 v126, 0xbfb8aa3b, v93
	v_exp_f32_e32 v115, v115
	v_exp_f32_e32 v120, v120
	v_exp_f32_e32 v121, v121
	v_exp_f32_e32 v122, v122
	v_exp_f32_e32 v123, v123
	v_exp_f32_e32 v124, v124
	v_exp_f32_e32 v125, v125
	v_exp_f32_e32 v126, v126
	v_add_f32_e32 v115, 1.0, v115
	v_add_f32_e32 v127, 1.0, v120
	v_add_f32_e32 v128, 1.0, v121
	v_add_f32_e32 v129, 1.0, v122
	v_add_f32_e32 v130, 1.0, v123
	v_add_f32_e32 v131, 1.0, v124
	v_add_f32_e32 v132, 1.0, v125
	v_add_f32_e32 v133, 1.0, v126
	v_rcp_f32_e32 v120, v115
	v_rcp_f32_e32 v121, v127
	v_rcp_f32_e32 v122, v128
	v_rcp_f32_e32 v123, v129
	v_rcp_f32_e32 v124, v130
	v_rcp_f32_e32 v125, v131
	v_rcp_f32_e32 v126, v132
	v_rcp_f32_e32 v127, v133
	v_pk_mul_f32 v[94:95], v[94:95], v[120:121]
	v_pk_mul_f32 v[90:91], v[90:91], v[122:123]
	v_pk_mul_f32 v[96:97], v[96:97], v[124:125]
	v_pk_mul_f32 v[92:93], v[92:93], v[126:127]
	v_pk_mul_f32 v[86:87], v[86:87], v[94:95]
	v_pk_mul_f32 v[90:91], v[82:83], v[90:91]
	v_pk_mul_f32 v[88:89], v[88:89], v[96:97]
	v_pk_mul_f32 v[92:93], v[84:85], v[92:93]
	v_cvt_pk_bf16_f32 v82, v86, v87
	v_cvt_pk_bf16_f32 v83, v88, v89
	v_cvt_pk_bf16_f32 v84, v90, v91
	v_cvt_pk_bf16_f32 v85, v92, v93
	global_store_dwordx4 v[116:117], v[82:85], off nt
	s_nop 0
	s_nop 0
	v_fmamk_f32 v82, v201, 0x3a000000, v180
	v_mul_f32_e32 v83, 0x4b800000, v82
	v_cmp_gt_f32_e32 vcc, s48, v82
	s_nop 1
	v_cndmask_b32_e32 v82, v82, v83, vcc
	v_rsq_f32_e32 v84, v82
	v_mad_i64_i32 v[82:83], s[6:7], v114, s49, v[168:169]
	v_lshl_add_u64 v[82:83], v[82:83], 0, v[170:171]
	v_mul_f32_e32 v85, 0x45800000, v84
	v_cndmask_b32_e32 v84, v84, v85, vcc
	v_pk_fma_f32 v[78:79], v[78:79], v[84:85], v[102:103] op_sel_hi:[1,0,1]
	v_pk_fma_f32 v[74:75], v[74:75], v[84:85], v[98:99] op_sel_hi:[1,0,1]
	v_pk_fma_f32 v[80:81], v[80:81], v[84:85], v[104:105] op_sel_hi:[1,0,1]
	v_pk_fma_f32 v[76:77], v[76:77], v[84:85], v[100:101] op_sel_hi:[1,0,1]
	v_pk_fma_f32 v[70:71], v[70:71], v[84:85], v[110:111] op_sel_hi:[1,0,1]
	v_pk_fma_f32 v[66:67], v[66:67], v[84:85], v[106:107] op_sel_hi:[1,0,1]
	v_pk_fma_f32 v[72:73], v[72:73], v[84:85], v[112:113] op_sel_hi:[1,0,1]
	v_pk_fma_f32 v[68:69], v[68:69], v[84:85], v[108:109] op_sel_hi:[1,0,1]
	v_mul_f32_e32 v84, 0xbfb8aa3b, v78
	v_mul_f32_e32 v85, 0xbfb8aa3b, v79
	v_mul_f32_e32 v86, 0xbfb8aa3b, v74
	v_mul_f32_e32 v87, 0xbfb8aa3b, v75
	v_mul_f32_e32 v88, 0xbfb8aa3b, v80
	v_mul_f32_e32 v89, 0xbfb8aa3b, v81
	v_mul_f32_e32 v90, 0xbfb8aa3b, v76
	v_mul_f32_e32 v91, 0xbfb8aa3b, v77
	v_exp_f32_e32 v84, v84
	v_exp_f32_e32 v85, v85
	v_exp_f32_e32 v86, v86
	v_exp_f32_e32 v87, v87
	v_exp_f32_e32 v88, v88
	v_exp_f32_e32 v89, v89
	v_exp_f32_e32 v90, v90
	v_exp_f32_e32 v91, v91
	v_add_f32_e32 v84, 1.0, v84
	v_add_f32_e32 v85, 1.0, v85
	v_add_f32_e32 v86, 1.0, v86
	v_add_f32_e32 v87, 1.0, v87
	v_add_f32_e32 v88, 1.0, v88
	v_add_f32_e32 v89, 1.0, v89
	v_add_f32_e32 v90, 1.0, v90
	v_add_f32_e32 v91, 1.0, v91
	v_rcp_f32_e32 v84, v84
	v_rcp_f32_e32 v85, v85
	v_rcp_f32_e32 v86, v86
	v_rcp_f32_e32 v87, v87
	v_rcp_f32_e32 v88, v88
	v_rcp_f32_e32 v89, v89
	v_rcp_f32_e32 v90, v90
	v_rcp_f32_e32 v91, v91
	v_pk_mul_f32 v[78:79], v[78:79], v[84:85]
	v_pk_mul_f32 v[74:75], v[74:75], v[86:87]
	v_pk_mul_f32 v[80:81], v[80:81], v[88:89]
	v_pk_mul_f32 v[76:77], v[76:77], v[90:91]
	v_pk_mul_f32 v[70:71], v[70:71], v[78:79]
	v_pk_mul_f32 v[74:75], v[66:67], v[74:75]
	v_pk_mul_f32 v[72:73], v[72:73], v[80:81]
	v_pk_mul_f32 v[76:77], v[68:69], v[76:77]
	v_cvt_pk_bf16_f32 v66, v70, v71
	v_cvt_pk_bf16_f32 v67, v72, v73
	v_cvt_pk_bf16_f32 v68, v74, v75
	v_cvt_pk_bf16_f32 v69, v76, v77
	global_store_dwordx4 v[82:83], v[66:69], off nt
	s_nop 0
	s_nop 0
	v_add_u32_e32 v67, 0x80, v164
	s_nop 0
	v_fmamk_f32 v66, v202, 0x3a000000, v180
	v_mul_f32_e32 v68, 0x4b800000, v66
	v_cmp_gt_f32_e32 vcc, s48, v66
	s_nop 1
	v_cndmask_b32_e32 v66, v66, v68, vcc
	v_rsq_f32_e32 v68, v66
	v_mad_i64_i32 v[66:67], s[6:7], v67, s49, v[168:169]
	v_lshl_add_u64 v[66:67], v[66:67], 0, v[170:171]
	v_mul_f32_e32 v69, 0x45800000, v68
	v_cndmask_b32_e32 v68, v68, v69, vcc
	v_pk_fma_f32 v[62:63], v[62:63], v[68:69], v[102:103] op_sel_hi:[1,0,1]
	v_pk_fma_f32 v[58:59], v[58:59], v[68:69], v[98:99] op_sel_hi:[1,0,1]
	v_pk_fma_f32 v[64:65], v[64:65], v[68:69], v[104:105] op_sel_hi:[1,0,1]
	v_pk_fma_f32 v[60:61], v[60:61], v[68:69], v[100:101] op_sel_hi:[1,0,1]
	v_pk_fma_f32 v[54:55], v[54:55], v[68:69], v[110:111] op_sel_hi:[1,0,1]
	v_pk_fma_f32 v[50:51], v[50:51], v[68:69], v[106:107] op_sel_hi:[1,0,1]
	v_pk_fma_f32 v[56:57], v[56:57], v[68:69], v[112:113] op_sel_hi:[1,0,1]
	v_pk_fma_f32 v[52:53], v[52:53], v[68:69], v[108:109] op_sel_hi:[1,0,1]
	v_mul_f32_e32 v68, 0xbfb8aa3b, v62
	v_mul_f32_e32 v69, 0xbfb8aa3b, v63
	v_mul_f32_e32 v70, 0xbfb8aa3b, v58
	v_mul_f32_e32 v71, 0xbfb8aa3b, v59
	v_mul_f32_e32 v72, 0xbfb8aa3b, v64
	v_mul_f32_e32 v73, 0xbfb8aa3b, v65
	v_mul_f32_e32 v74, 0xbfb8aa3b, v60
	v_mul_f32_e32 v75, 0xbfb8aa3b, v61
	v_exp_f32_e32 v68, v68
	v_exp_f32_e32 v69, v69
	v_exp_f32_e32 v70, v70
	v_exp_f32_e32 v71, v71
	v_exp_f32_e32 v72, v72
	v_exp_f32_e32 v73, v73
	v_exp_f32_e32 v74, v74
	v_exp_f32_e32 v75, v75
	v_add_f32_e32 v68, 1.0, v68
	v_add_f32_e32 v69, 1.0, v69
	v_add_f32_e32 v70, 1.0, v70
	v_add_f32_e32 v71, 1.0, v71
	v_add_f32_e32 v72, 1.0, v72
	v_add_f32_e32 v73, 1.0, v73
	v_add_f32_e32 v74, 1.0, v74
	v_add_f32_e32 v75, 1.0, v75
	v_rcp_f32_e32 v68, v68
	v_rcp_f32_e32 v69, v69
	v_rcp_f32_e32 v70, v70
	v_rcp_f32_e32 v71, v71
	v_rcp_f32_e32 v72, v72
	v_rcp_f32_e32 v73, v73
	v_rcp_f32_e32 v74, v74
	v_rcp_f32_e32 v75, v75
	v_pk_mul_f32 v[62:63], v[62:63], v[68:69]
	v_pk_mul_f32 v[58:59], v[58:59], v[70:71]
	v_pk_mul_f32 v[64:65], v[64:65], v[72:73]
	v_pk_mul_f32 v[60:61], v[60:61], v[74:75]
	v_pk_mul_f32 v[54:55], v[54:55], v[62:63]
	v_pk_mul_f32 v[58:59], v[50:51], v[58:59]
	v_pk_mul_f32 v[56:57], v[56:57], v[64:65]
	v_pk_mul_f32 v[60:61], v[52:53], v[60:61]
	v_cvt_pk_bf16_f32 v50, v54, v55
	v_cvt_pk_bf16_f32 v51, v56, v57
	v_cvt_pk_bf16_f32 v52, v58, v59
	v_cvt_pk_bf16_f32 v53, v60, v61
	global_store_dwordx4 v[66:67], v[50:53], off nt
	s_nop 0
	s_nop 0
	v_add_u32_e32 v51, 0x90, v164
	s_nop 0
	v_fmamk_f32 v50, v203, 0x3a000000, v180
	v_mul_f32_e32 v52, 0x4b800000, v50
	v_cmp_gt_f32_e32 vcc, s48, v50
	s_nop 1
	v_cndmask_b32_e32 v50, v50, v52, vcc
	v_rsq_f32_e32 v52, v50
	v_mad_i64_i32 v[50:51], s[6:7], v51, s49, v[168:169]
	v_lshl_add_u64 v[50:51], v[50:51], 0, v[170:171]
	v_mul_f32_e32 v53, 0x45800000, v52
	v_cndmask_b32_e32 v52, v52, v53, vcc
	v_pk_fma_f32 v[46:47], v[46:47], v[52:53], v[102:103] op_sel_hi:[1,0,1]
	v_pk_fma_f32 v[42:43], v[42:43], v[52:53], v[98:99] op_sel_hi:[1,0,1]
	v_pk_fma_f32 v[48:49], v[48:49], v[52:53], v[104:105] op_sel_hi:[1,0,1]
	v_pk_fma_f32 v[44:45], v[44:45], v[52:53], v[100:101] op_sel_hi:[1,0,1]
	v_pk_fma_f32 v[38:39], v[38:39], v[52:53], v[110:111] op_sel_hi:[1,0,1]
	v_pk_fma_f32 v[34:35], v[34:35], v[52:53], v[106:107] op_sel_hi:[1,0,1]
	v_pk_fma_f32 v[40:41], v[40:41], v[52:53], v[112:113] op_sel_hi:[1,0,1]
	v_pk_fma_f32 v[36:37], v[36:37], v[52:53], v[108:109] op_sel_hi:[1,0,1]
	v_mul_f32_e32 v52, 0xbfb8aa3b, v46
	v_mul_f32_e32 v53, 0xbfb8aa3b, v47
	v_mul_f32_e32 v54, 0xbfb8aa3b, v42
	v_mul_f32_e32 v55, 0xbfb8aa3b, v43
	v_mul_f32_e32 v56, 0xbfb8aa3b, v48
	v_mul_f32_e32 v57, 0xbfb8aa3b, v49
	v_mul_f32_e32 v58, 0xbfb8aa3b, v44
	v_mul_f32_e32 v59, 0xbfb8aa3b, v45
	v_exp_f32_e32 v52, v52
	v_exp_f32_e32 v53, v53
	v_exp_f32_e32 v54, v54
	v_exp_f32_e32 v55, v55
	v_exp_f32_e32 v56, v56
	v_exp_f32_e32 v57, v57
	v_exp_f32_e32 v58, v58
	v_exp_f32_e32 v59, v59
	v_add_f32_e32 v52, 1.0, v52
	v_add_f32_e32 v53, 1.0, v53
	v_add_f32_e32 v54, 1.0, v54
	v_add_f32_e32 v55, 1.0, v55
	v_add_f32_e32 v56, 1.0, v56
	v_add_f32_e32 v57, 1.0, v57
	v_add_f32_e32 v58, 1.0, v58
	v_add_f32_e32 v59, 1.0, v59
	v_rcp_f32_e32 v52, v52
	v_rcp_f32_e32 v53, v53
	v_rcp_f32_e32 v54, v54
	v_rcp_f32_e32 v55, v55
	v_rcp_f32_e32 v56, v56
	v_rcp_f32_e32 v57, v57
	v_rcp_f32_e32 v58, v58
	v_rcp_f32_e32 v59, v59
	v_pk_mul_f32 v[46:47], v[46:47], v[52:53]
	v_pk_mul_f32 v[42:43], v[42:43], v[54:55]
	v_pk_mul_f32 v[48:49], v[48:49], v[56:57]
	v_pk_mul_f32 v[44:45], v[44:45], v[58:59]
	v_pk_mul_f32 v[38:39], v[38:39], v[46:47]
	v_pk_mul_f32 v[42:43], v[34:35], v[42:43]
	v_pk_mul_f32 v[40:41], v[40:41], v[48:49]
	v_pk_mul_f32 v[44:45], v[36:37], v[44:45]
	v_cvt_pk_bf16_f32 v34, v38, v39
	v_cvt_pk_bf16_f32 v35, v40, v41
	v_cvt_pk_bf16_f32 v36, v42, v43
	v_cvt_pk_bf16_f32 v37, v44, v45
	global_store_dwordx4 v[50:51], v[34:37], off nt
	s_nop 0
	s_nop 0
	v_add_u32_e32 v35, 0xa0, v164
	s_nop 0
	v_fmamk_f32 v34, v204, 0x3a000000, v180
	v_mul_f32_e32 v36, 0x4b800000, v34
	v_cmp_gt_f32_e32 vcc, s48, v34
	s_nop 1
	v_cndmask_b32_e32 v34, v34, v36, vcc
	v_rsq_f32_e32 v36, v34
	v_mad_i64_i32 v[34:35], s[6:7], v35, s49, v[168:169]
	v_lshl_add_u64 v[34:35], v[34:35], 0, v[170:171]
	v_mul_f32_e32 v37, 0x45800000, v36
	v_cndmask_b32_e32 v36, v36, v37, vcc
	v_pk_fma_f32 v[30:31], v[30:31], v[36:37], v[102:103] op_sel_hi:[1,0,1]
	v_pk_fma_f32 v[26:27], v[26:27], v[36:37], v[98:99] op_sel_hi:[1,0,1]
	v_pk_fma_f32 v[32:33], v[32:33], v[36:37], v[104:105] op_sel_hi:[1,0,1]
	v_pk_fma_f32 v[28:29], v[28:29], v[36:37], v[100:101] op_sel_hi:[1,0,1]
	v_pk_fma_f32 v[22:23], v[22:23], v[36:37], v[110:111] op_sel_hi:[1,0,1]
	v_pk_fma_f32 v[18:19], v[18:19], v[36:37], v[106:107] op_sel_hi:[1,0,1]
	v_pk_fma_f32 v[24:25], v[24:25], v[36:37], v[112:113] op_sel_hi:[1,0,1]
	v_pk_fma_f32 v[20:21], v[20:21], v[36:37], v[108:109] op_sel_hi:[1,0,1]
	v_mul_f32_e32 v36, 0xbfb8aa3b, v30
	v_mul_f32_e32 v37, 0xbfb8aa3b, v31
	v_mul_f32_e32 v38, 0xbfb8aa3b, v26
	v_mul_f32_e32 v39, 0xbfb8aa3b, v27
	v_mul_f32_e32 v40, 0xbfb8aa3b, v32
	v_mul_f32_e32 v41, 0xbfb8aa3b, v33
	v_mul_f32_e32 v42, 0xbfb8aa3b, v28
	v_mul_f32_e32 v43, 0xbfb8aa3b, v29
	v_exp_f32_e32 v36, v36
	v_exp_f32_e32 v37, v37
	v_exp_f32_e32 v38, v38
	v_exp_f32_e32 v39, v39
	v_exp_f32_e32 v40, v40
	v_exp_f32_e32 v41, v41
	v_exp_f32_e32 v42, v42
	v_exp_f32_e32 v43, v43
	v_add_f32_e32 v36, 1.0, v36
	v_add_f32_e32 v37, 1.0, v37
	v_add_f32_e32 v38, 1.0, v38
	v_add_f32_e32 v39, 1.0, v39
	v_add_f32_e32 v40, 1.0, v40
	v_add_f32_e32 v41, 1.0, v41
	v_add_f32_e32 v42, 1.0, v42
	v_add_f32_e32 v43, 1.0, v43
	v_rcp_f32_e32 v36, v36
	v_rcp_f32_e32 v37, v37
	v_rcp_f32_e32 v38, v38
	v_rcp_f32_e32 v39, v39
	v_rcp_f32_e32 v40, v40
	v_rcp_f32_e32 v41, v41
	v_rcp_f32_e32 v42, v42
	v_rcp_f32_e32 v43, v43
	v_pk_mul_f32 v[30:31], v[30:31], v[36:37]
	v_pk_mul_f32 v[26:27], v[26:27], v[38:39]
	v_pk_mul_f32 v[32:33], v[32:33], v[40:41]
	v_pk_mul_f32 v[28:29], v[28:29], v[42:43]
	v_pk_mul_f32 v[22:23], v[22:23], v[30:31]
	v_pk_mul_f32 v[26:27], v[18:19], v[26:27]
	v_pk_mul_f32 v[24:25], v[24:25], v[32:33]
	v_pk_mul_f32 v[28:29], v[20:21], v[28:29]
	v_cvt_pk_bf16_f32 v18, v22, v23
	v_cvt_pk_bf16_f32 v19, v24, v25
	v_cvt_pk_bf16_f32 v20, v26, v27
	v_cvt_pk_bf16_f32 v21, v28, v29
	global_store_dwordx4 v[34:35], v[18:21], off nt
	s_nop 0
	s_andn2_b64 vcc, exec, s[0:1]
	v_add_u32_e32 v19, 0xb0, v164
	s_mov_b64 s[0:1], -1
	s_nop 0
	v_fmamk_f32 v18, v205, 0x3a000000, v180
	v_mul_f32_e32 v20, 0x4b800000, v18
	v_cmp_gt_f32_e64 s[6:7], s48, v18
	s_nop 1
	v_cndmask_b32_e64 v18, v18, v20, s[6:7]
	v_rsq_f32_e32 v20, v18
	v_mad_i64_i32 v[18:19], s[26:27], v19, s49, v[168:169]
	v_lshl_add_u64 v[18:19], v[18:19], 0, v[170:171]
	v_mul_f32_e32 v21, 0x45800000, v20
	v_cndmask_b32_e64 v20, v20, v21, s[6:7]
	v_pk_fma_f32 v[14:15], v[14:15], v[20:21], v[102:103] op_sel_hi:[1,0,1]
	v_pk_fma_f32 v[10:11], v[10:11], v[20:21], v[98:99] op_sel_hi:[1,0,1]
	v_pk_fma_f32 v[16:17], v[16:17], v[20:21], v[104:105] op_sel_hi:[1,0,1]
	v_pk_fma_f32 v[12:13], v[12:13], v[20:21], v[100:101] op_sel_hi:[1,0,1]
	v_pk_fma_f32 v[6:7], v[6:7], v[20:21], v[110:111] op_sel_hi:[1,0,1]
	v_pk_fma_f32 v[2:3], v[2:3], v[20:21], v[106:107] op_sel_hi:[1,0,1]
	v_pk_fma_f32 v[8:9], v[8:9], v[20:21], v[112:113] op_sel_hi:[1,0,1]
	v_pk_fma_f32 v[4:5], v[4:5], v[20:21], v[108:109] op_sel_hi:[1,0,1]
	v_mul_f32_e32 v20, 0xbfb8aa3b, v14
	v_mul_f32_e32 v21, 0xbfb8aa3b, v15
	v_mul_f32_e32 v22, 0xbfb8aa3b, v10
	v_mul_f32_e32 v23, 0xbfb8aa3b, v11
	v_mul_f32_e32 v24, 0xbfb8aa3b, v16
	v_mul_f32_e32 v25, 0xbfb8aa3b, v17
	v_mul_f32_e32 v26, 0xbfb8aa3b, v12
	v_mul_f32_e32 v27, 0xbfb8aa3b, v13
	v_exp_f32_e32 v20, v20
	v_exp_f32_e32 v21, v21
	v_exp_f32_e32 v22, v22
	v_exp_f32_e32 v23, v23
	v_exp_f32_e32 v24, v24
	v_exp_f32_e32 v25, v25
	v_exp_f32_e32 v26, v26
	v_exp_f32_e32 v27, v27
	v_add_f32_e32 v20, 1.0, v20
	v_add_f32_e32 v21, 1.0, v21
	v_add_f32_e32 v22, 1.0, v22
	v_add_f32_e32 v23, 1.0, v23
	v_add_f32_e32 v24, 1.0, v24
	v_add_f32_e32 v25, 1.0, v25
	v_add_f32_e32 v26, 1.0, v26
	v_add_f32_e32 v27, 1.0, v27
	v_rcp_f32_e32 v20, v20
	v_rcp_f32_e32 v21, v21
	v_rcp_f32_e32 v22, v22
	v_rcp_f32_e32 v23, v23
	v_rcp_f32_e32 v24, v24
	v_rcp_f32_e32 v25, v25
	v_rcp_f32_e32 v26, v26
	v_rcp_f32_e32 v27, v27
	v_pk_mul_f32 v[14:15], v[14:15], v[20:21]
	v_pk_mul_f32 v[10:11], v[10:11], v[22:23]
	v_pk_mul_f32 v[16:17], v[16:17], v[24:25]
	v_pk_mul_f32 v[12:13], v[12:13], v[26:27]
	v_pk_mul_f32 v[6:7], v[6:7], v[14:15]
	v_pk_mul_f32 v[10:11], v[2:3], v[10:11]
	v_pk_mul_f32 v[8:9], v[8:9], v[16:17]
	v_pk_mul_f32 v[12:13], v[4:5], v[12:13]
	v_cvt_pk_bf16_f32 v2, v6, v7
	v_cvt_pk_bf16_f32 v3, v8, v9
	v_cvt_pk_bf16_f32 v4, v10, v11
	v_cvt_pk_bf16_f32 v5, v12, v13
	global_store_dwordx4 v[18:19], v[2:5], off nt
	s_cbranch_vccnz .LBB0_1204
	s_andn2_b64 vcc, exec, s[2:3]
	s_cbranch_vccnz .LBB0_1203
	s_barrier
	s_branch .LBB0_1203
